# v7: all grid barriers poll the top generation word; barrier 3 split too with the z_p projection K-loop of the j>=2 workgroups moved ahead of their mLSTM output units into the barrier shadow
# speedup vs baseline: 1.0396x; 1.0126x over previous
; __device__ __forceinline__ unsigned xb_ld(unsigned* p)              { return __hip_atomic_load(p, __ATOMIC_RELAXED, __HIP_MEMORY_SCOPE_AGENT); }
; __device__ __forceinline__ unsigned xb_add(unsigned* p, unsigned v) { return __hip_atomic_fetch_add(p, v, __ATOMIC_RELAXED, __HIP_MEMORY_SCOPE_AGENT); }
; __device__ __forceinline__ void xcd_barrier_complete(unsigned* bar, unsigned x, unsigned& nloc, unsigned& nx) {
;     const unsigned G = gridDim.x * gridDim.y * gridDim.z;
;     unsigned sum, cnt, mine, sp = 0u;
;     for (;;) {
;         sum = 0u; cnt = 0u; mine = 0u;
; #pragma unroll
;         for (unsigned j = 0; j < 16; ++j) { const unsigned c = xb_ld(&bar[XB_XCNT(j)]); sum += c; cnt += (c > 0u) ? 1u : 0u; mine = (j == x) ? c : mine; }
;         if (sum == G) break;
;         __builtin_amdgcn_s_sleep(1);
;         if ((++sp & 255u) == 0u) { if (xb_ld(&bar[XB_TMO])) break; if (sp > XB_SPIN_CAP) { atomicAdd(&bar[XB_TMO], 1u); break; } }
;     }
;     nloc = mine > 0u ? mine : 1u; nx = cnt > 0u ? cnt : 1u;
; }
; __device__ __forceinline__ void xcd_barrier(const XcdBarrier& b) {
;     asm volatile("s_waitcnt vmcnt(0)" ::: "memory");
;     __syncthreads();
;     if (threadIdx.x == 0) {
;         unsigned* bar = b.bar;
;         __builtin_amdgcn_s_waitcnt(0);
;         unsigned nloc = b.st[0], nx = b.st[1];
;         if (nloc == 0u) { xcd_barrier_complete(bar, b.x, nloc, nx); b.st[0] = nloc; b.st[1] = nx; }
;         const unsigned old = xb_add(&bar[XB_XSUB(b.x)], 1u);
;         const unsigned gen = old / nloc;
;         if (old + 1u == (gen + 1u) * nloc) {
;             __builtin_amdgcn_fence(__ATOMIC_RELEASE, "agent");
;             asm volatile("s_waitcnt vmcnt(0)" ::: "memory");
;             const unsigned og = xb_add(&bar[XB_TOP], 1u);
;             const unsigned tg = og / nx;
;             if (og + 1u == (tg + 1u) * nx) xb_add(&bar[XB_TOPGEN], 1u);
;             else XB_SPIN(xb_ld(&bar[XB_TOPGEN]) == tg, bar);
;             __builtin_amdgcn_fence(__ATOMIC_ACQUIRE, "agent");
;             xb_add(&bar[XB_XGEN(b.x)], 1u);
;             asm volatile("s_waitcnt vmcnt(0)" ::: "memory");
;         } else {
;             XB_SPIN(xb_ld(&bar[XB_XGEN(b.x)]) == gen, bar);
;             __builtin_amdgcn_fence(__ATOMIC_ACQUIRE, "agent");
;             asm volatile("s_waitcnt vmcnt(0)" ::: "memory");
;         }
.LBB0_131:
	s_or_b64 exec, exec, s[8:9]
	v_cvt_f32_u32_e32 v4, v2
	s_waitcnt vmcnt(0)
	v_readfirstlane_b32 s3, v3
	v_sub_u32_e32 v3, 0, v2
	v_rcp_iflag_f32_e32 v4, v4
	v_add_u32_e32 v5, s3, v1
	v_mul_f32_e32 v4, 0x4f7ffffe, v4
	v_cvt_u32_f32_e32 v4, v4
	v_mul_lo_u32 v1, v3, v4
	v_mul_hi_u32 v1, v4, v1
	v_add_u32_e32 v1, v4, v1
	v_mul_hi_u32 v1, v5, v1
	v_mul_lo_u32 v3, v1, v2
	v_sub_u32_e32 v3, v5, v3
	v_add_u32_e32 v4, 1, v1
	v_cmp_ge_u32_e32 vcc, v3, v2
	s_nop 1
	v_cndmask_b32_e32 v1, v1, v4, vcc
	v_sub_u32_e32 v4, v3, v2
	v_cndmask_b32_e32 v3, v3, v4, vcc
	v_add_u32_e32 v4, 1, v1
	v_cmp_ge_u32_e32 vcc, v3, v2
	v_add_u32_e32 v3, 1, v5
	s_nop 0
	v_cndmask_b32_e32 v1, v1, v4, vcc
	v_mul_lo_u32 v4, v2, v1
	v_add_u32_e32 v2, v4, v2
	v_cmp_ne_u32_e32 vcc, v3, v2
	s_and_saveexec_b64 s[6:7], vcc
	s_xor_b64 s[6:7], exec, s[6:7]
	s_cbranch_execz .LBB0_145
.LBB0_145:
	s_andn2_saveexec_b64 s[6:7], s[6:7]
	s_cbranch_execz .LBB0_165
	s_mov_b64 s[6:7], exec
	buffer_wbl2 sc1
	s_waitcnt lgkmcnt(0)
	s_waitcnt vmcnt(0)
	v_mbcnt_lo_u32_b32 v1, s6, 0
	v_mbcnt_hi_u32_b32 v1, s7, v1
	v_cmp_eq_u32_e32 vcc, 0, v1
	s_and_saveexec_b64 s[8:9], vcc
	s_cbranch_execz .LBB0_148
	s_bcnt1_i32_b64 s3, s[6:7]
	v_mov_b32_e32 v2, 0xff83000
	v_mov_b32_e32 v3, s3
	global_atomic_add v2, v2, v3, s[70:71] offset:1024 sc0
.LBB0_148:
	s_or_b64 exec, exec, s[8:9]
	v_cvt_f32_u32_e32 v3, v0
	s_waitcnt vmcnt(0)
	v_readfirstlane_b32 s3, v2
	s_add_u32 s8, s70, 0xff83500
	s_addc_u32 s9, s71, 0
	v_rcp_iflag_f32_e32 v3, v3
	v_add_u32_e32 v1, s3, v1
	v_add_u32_e32 v4, 1, v1
	s_mov_b64 s[10:11], -1
	v_mul_f32_e32 v2, 0x4f7ffffe, v3
	v_cvt_u32_f32_e32 v2, v2
	v_sub_u32_e32 v3, 0, v0
	v_mul_lo_u32 v3, v3, v2
	v_mul_hi_u32 v3, v2, v3
	v_add_u32_e32 v2, v2, v3
	v_mul_hi_u32 v2, v1, v2
	v_mul_lo_u32 v3, v2, v0
	v_sub_u32_e32 v1, v1, v3
	v_add_u32_e32 v5, 1, v2
	v_cmp_ge_u32_e32 vcc, v1, v0
	v_sub_u32_e32 v3, v1, v0
	s_nop 0
	v_cndmask_b32_e32 v2, v2, v5, vcc
	v_cndmask_b32_e32 v1, v1, v3, vcc
	v_add_u32_e32 v3, 1, v2
	v_cmp_ge_u32_e32 vcc, v1, v0
	s_nop 1
	v_cndmask_b32_e32 v2, v2, v3, vcc
	v_mul_lo_u32 v1, v0, v2
	v_add_u32_e32 v0, v1, v0
	v_cmp_ne_u32_e32 vcc, v4, v0
	v_mov_b64_e32 v[0:1], s[8:9]
	s_and_saveexec_b64 s[6:7], vcc
	s_cbranch_execz .LBB0_160
	s_andn2_b64 s[10:11], s[10:11], exec

; __device__ __forceinline__ unsigned xb_ld(unsigned* p)              { return __hip_atomic_load(p, __ATOMIC_RELAXED, __HIP_MEMORY_SCOPE_AGENT); }
; __device__ __forceinline__ unsigned xb_add(unsigned* p, unsigned v) { return __hip_atomic_fetch_add(p, v, __ATOMIC_RELAXED, __HIP_MEMORY_SCOPE_AGENT); }
; #define XB_SPIN(cond, bar) do { unsigned _sp = 0; while (cond) { __builtin_amdgcn_s_sleep(1); \
;     if ((++_sp & 255u) == 0u) { if (xb_ld(&(bar)[XB_TMO])) break; if (_sp > XB_SPIN_CAP) { atomicAdd(&(bar)[XB_TMO], 1u); break; } } } } while (0)
; __device__ __forceinline__ void xcd_barrier(const XcdBarrier& b) {
;     ...
;             __builtin_amdgcn_fence(__ATOMIC_RELEASE, "agent");
;             asm volatile("s_waitcnt vmcnt(0)" ::: "memory");
;             const unsigned og = xb_add(&bar[XB_TOP], 1u);
;             const unsigned tg = og / nx;
;             if (og + 1u == (tg + 1u) * nx) xb_add(&bar[XB_TOPGEN], 1u);
;             else XB_SPIN(xb_ld(&bar[XB_TOPGEN]) == tg, bar);
;             __builtin_amdgcn_fence(__ATOMIC_ACQUIRE, "agent");
;             xb_add(&bar[XB_XGEN(b.x)], 1u);
;             asm volatile("s_waitcnt vmcnt(0)" ::: "memory");
.LBB0_162:
	s_or_b64 exec, exec, s[6:7]
	s_mov_b64 s[6:7], exec
	v_mbcnt_lo_u32_b32 v0, s6, 0
	v_mbcnt_hi_u32_b32 v0, s7, v0
	v_cmp_eq_u32_e32 vcc, 0, v0
	s_waitcnt vmcnt(0)
	s_and_saveexec_b64 s[8:9], vcc
	s_cbranch_execz .LBB0_164
	s_bcnt1_i32_b64 s3, s[6:7]
	v_mov_b32_e32 v0, 0x2000
	v_mov_b32_e32 v1, s3
	global_atomic_add v0, v1, s[4:5] offset:1024

; __device__ __forceinline__ unsigned xb_ld(unsigned* p)              { return __hip_atomic_load(p, __ATOMIC_RELAXED, __HIP_MEMORY_SCOPE_AGENT); }
; #define XB_SPIN(cond, bar) do { unsigned _sp = 0; while (cond) { __builtin_amdgcn_s_sleep(1); \
;     if ((++_sp & 255u) == 0u) { if (xb_ld(&(bar)[XB_TMO])) break; if (_sp > XB_SPIN_CAP) { atomicAdd(&(bar)[XB_TMO], 1u); break; } } } } while (0)
; __device__ __forceinline__ void xcd_barrier(const XcdBarrier& b) {
;     ...
;             XB_SPIN(xb_ld(&bar[XB_XGEN(b.x)]) == gen, bar);
;             __builtin_amdgcn_fence(__ATOMIC_ACQUIRE, "agent");
;             asm volatile("s_waitcnt vmcnt(0)" ::: "memory");
;         }
;     }
;     __syncthreads();
.LBB0_165:
	s_or_b64 exec, exec, s[0:1]
	s_waitcnt lgkmcnt(0)
	v_mov_b32_e32 v0, v224
	v_mov_b32_e32 v14, v224
	v_cmp_eq_u32_e32 vcc, 0, v224
	s_and_saveexec_b64 s[42:43], vcc
	s_cbranch_execz .Lgb1_done
	s_add_u32 s38, s70, 0xff83500
	s_addc_u32 s39, s71, 0
	s_mov_b32 s40, 0x8000
	v_mov_b32_e32 v250, 0
.Lgb1_spin:
	global_load_dword v251, v250, s[38:39] sc1
	s_waitcnt vmcnt(0)
	v_readfirstlane_b32 s41, v251
	s_cmp_ge_u32 s41, 1
	s_cbranch_scc1 .Lgb1_ok
	s_sleep 1
	s_sub_u32 s40, s40, 1
	s_cmp_lg_u32 s40, 0
	s_cbranch_scc1 .Lgb1_spin

; __device__ __forceinline__ int opaque_tid() { int t = (int)threadIdx.x; asm volatile("" : "+v"(t)); return t; }
; #define PG8_STAGE(bufoff, gbase, voff) do { _Pragma("unroll") for (int _i = 0; _i < 2; ++_i) \
;         __builtin_amdgcn_global_load_lds((const unsigned*)((const char*)(gbase) + (voff)[_i]), (LAS unsigned*)(lds + (bufoff) + ldsw + _i * 8192), 16, 0, 0); } while (0)
; #define PG8_WAIT_V(n) asm volatile("s_waitcnt vmcnt(" #n ")" ::: "memory")
; #define PG8_BAR __builtin_amdgcn_s_barrier()
; template <class Epi, class Sched, bool ZERO>
; __device__ __forceinline__ void gemm_phase_acc(LAS unsigned char* lds, const Gemm g, const Sched& S, const Epi& E, f32x4 (&acc)[2][2][4][2]) {
;     const int tid = opaque_tid(), wid = __builtin_amdgcn_readfirstlane(tid >> 6), lane = tid & 63, wr = wid >> 2, wc = wid & 3, fr = lane & 15, fq = lane >> 4;
;     const int K = g.K, nt = K / BK;
;     unsigned voffA[2], voffB[2];
; #pragma unroll
;     for (int i = 0; i < 2; ++i) { int R, C; stage_rc(tid * 16 + i * 8192, R, C); const int Rb = (R & ~31) + perm32(R & 31);
;         voffA[i] = (unsigned)(R * K + C) * 2u; voffB[i] = (unsigned)(Rb * K + C) * 2u; }
;     const size_t kstep = (size_t)(BK * 2);
;     const size_t hstep = (size_t)HALF * K * 2;
;     const size_t tstep = 2 * hstep;
;     const unsigned ldsw = (unsigned)wid * 1024u;
;     const int aoff = lds_byte(wr * 64 + fr, fq * 8), boff = lds_byte(wc * 32 + fr, fq * 8);
;     ...
;     Unit cur, nxt; int ui = 0;
;     if (!S.next(0, cur)) return;
;     if constexpr (ZERO) {
; #pragma unroll
;     for (int a = 0; a < 2; ++a)
; #pragma unroll
;         for (int b = 0; b < 2; ++b)
; #pragma unroll
;             for (int m = 0; m < 4; ++m)
; #pragma unroll
;                 for (int n = 0; n < 2; ++n) acc[a][b][m][n] = (f32x4){0.f, 0.f, 0.f, 0.f};
;     }
;     bf16x8 At[4][2], B0[2][2], B1[2][2];
;     const char* cA = (const char*)g.A + (size_t)cur.pm * tstep; const char* cB = (const char*)g.Bt + (size_t)cur.pn * tstep;
;     PG8_STAGE(PG8_SB(0, 0), cB, voffB); PG8_STAGE(PG8_SA(0, 0), cA, voffA); PG8_STAGE(PG8_SB(0, 1), cB + hstep, voffB); PG8_STAGE(PG8_SA(0, 1), cA + hstep, voffA);
;     if (wr == 1) PG8_BAR;
;     PG8_WAIT_V(4); PG8_BAR;
;     PG8_STAGE(PG8_SB(1, 0), cB + kstep, voffB); PG8_STAGE(PG8_SA(1, 0), cA + kstep, voffA); PG8_STAGE(PG8_SB(1, 1), cB + hstep + kstep, voffB);
;     PG8_WAIT_V(6); PG8_BAR;
.Lgb1_done:
	s_or_b64 exec, exec, s[42:43]
	s_barrier
	s_mov_b32 s1, 0x1fffe0
	v_ashrrev_i32_e32 v1, 31, v14
	v_lshrrev_b32_e32 v1, 26, v1
	v_add_u32_e32 v1, v14, v1
	v_ashrrev_i32_e32 v8, 6, v1
	v_bfe_i32 v1, v14, 27, 1
	v_lshlrev_b32_e32 v0, 4, v14
	v_lshrrev_b32_e32 v1, 22, v1
	v_add_u32_e32 v1, v0, v1
	v_and_b32_e32 v1, 0xfffffc00, v1
	v_sub_u32_e32 v1, v0, v1
	v_lshrrev_b32_e32 v2, 4, v1
	v_bitop3_b32 v2, v2, v1, 32 bitop3:0x6c
	v_ashrrev_i32_e32 v1, 31, v1
	v_lshrrev_b32_e32 v1, 26, v1
	v_add_u32_e32 v1, v2, v1
	v_ashrrev_i32_e32 v9, 6, v1
	v_lshlrev_b32_e32 v3, 3, v8
	s_waitcnt vmcnt(1)
	v_mul_i32_i24_e32 v4, 64, v9
	v_and_b32_e32 v3, -16, v3
	v_sub_u32_e32 v2, v2, v4
	v_mov_b32_e32 v4, 1
	v_add_u32_e32 v1, v9, v3
	v_lshlrev_b32_e32 v3, 5, v8
	v_ashrrev_i16_sdwa v2, v4, sext(v2) dst_sel:DWORD dst_unused:UNUSED_PAD src0_sel:DWORD src1_sel:BYTE_0
	v_and_b32_e32 v3, 32, v3
	v_bfe_i32 v10, v2, 0, 16
	v_and_b32_e32 v6, 3, v9
	v_add_lshl_u32 v3, v3, v10, 1
	v_add_u32_e32 v0, 0x2000, v0
	v_lshlrev_b32_e32 v2, 1, v1
	v_lshrrev_b32_e32 v5, 2, v1
	v_and_or_b32 v6, v1, s1, v6
	v_lshl_add_u32 v128, v1, 11, v3
	v_ashrrev_i32_e32 v1, 31, v0
	v_lshrrev_b32_e32 v1, 22, v1
	v_add_u32_e32 v1, v0, v1
	v_ashrrev_i32_e32 v11, 10, v1
	v_mul_i32_i24_e32 v1, 0x400, v11
	v_sub_u32_e32 v0, v0, v1
	v_and_b32_e32 v2, 24, v2
	v_and_b32_e32 v5, 4, v5
	v_lshrrev_b32_e32 v1, 4, v0
	v_or3_b32 v2, v6, v5, v2
	v_bitop3_b32 v0, v1, v0, 32 bitop3:0x6c
	v_lshl_add_u32 v130, v2, 11, v3
	v_ashrrev_i32_e32 v2, 31, v0
	v_lshrrev_b32_e32 v2, 26, v2
	v_add_u32_e32 v2, v0, v2
	s_lshl_b32 s3, s2, 3
	v_lshlrev_b32_e32 v1, 3, v11
	v_ashrrev_i32_e32 v12, 6, v2
	v_and_b32_e32 v2, 0xc0, v2
	s_ashr_i32 s6, s2, 5
	s_and_b32 s3, s3, 56
	v_readfirstlane_b32 s41, v14
	v_and_b32_e32 v1, -16, v1
	v_sub_u32_e32 v0, v0, v2
	s_bfe_u32 s34, s2, 0x20003
	s_mov_b32 s4, s6
	s_add_i32 s18, s3, s6
	s_ashr_i32 s0, s41, 6
	v_add_u32_e32 v1, v12, v1
	v_ashrrev_i16_sdwa v0, v4, sext(v0) dst_sel:DWORD dst_unused:UNUSED_PAD src0_sel:DWORD src1_sel:BYTE_0
	v_and_b32_e32 v4, 3, v12
	v_writelane_b32 v254, s4, 24
	s_or_b32 s6, s34, 0x48
	s_ashr_i32 s19, s18, 31
	v_and_or_b32 v4, v1, s1, v4
	s_ashr_i32 s1, s41, 8
	s_lshl_b32 s26, s0, 10
	v_writelane_b32 v254, s5, 25
	s_lshl_b64 s[4:5], s[18:19], 19
	s_lshl_b32 s3, s6, 19
	s_add_u32 s14, s70, s3
	v_lshlrev_b32_e32 v3, 5, v11
	v_bfe_i32 v13, v0, 0, 16
	v_lshlrev_b32_e32 v0, 1, v1
	v_lshrrev_b32_e32 v2, 2, v1
	s_addc_u32 s15, s71, 0
	s_add_i32 s24, s26, 0
	v_and_b32_e32 v3, 32, v3
	v_and_b32_e32 v0, 24, v0
	v_and_b32_e32 v2, 4, v2
	s_add_i32 m0, s24, 0x10000
	v_or3_b32 v0, v4, v2, v0
	v_add_lshl_u32 v2, v3, v13, 1
	global_load_lds_dwordx4 v130, s[14:15]
	s_add_i32 m0, s24, 0x12000
	v_lshl_add_u32 v134, v0, 11, v2
	s_add_u32 s20, s70, s4
	global_load_lds_dwordx4 v134, s[14:15]
	v_writelane_b32 v254, s4, 26
	s_addc_u32 s21, s71, s5
	s_mov_b32 m0, s24
	s_add_i32 s25, s24, 0x2000
	v_lshl_add_u32 v132, v1, 11, v2
	v_writelane_b32 v254, s5, 27
	global_load_lds_dwordx4 v128, s[20:21]
	s_mov_b32 m0, s25
	s_add_u32 s4, s14, 0x40000
	global_load_lds_dwordx4 v132, s[20:21]
	s_addc_u32 s5, s15, 0
	s_add_i32 m0, s24, 0x14000
	v_mov_b32_e32 v137, 0
	global_load_lds_dwordx4 v130, s[4:5]
	s_add_i32 m0, s24, 0x16000
	v_mov_b32_e32 v131, v137
	global_load_lds_dwordx4 v134, s[4:5]
	s_add_u32 s4, s20, 0x40000
	s_addc_u32 s5, s21, 0
	s_add_i32 s28, s24, 0x4000
	s_mov_b32 m0, s28
	s_add_i32 s29, s24, 0x6000
	global_load_lds_dwordx4 v128, s[4:5]
	s_mov_b32 m0, s29
	v_writelane_b32 v254, s4, 28
	v_mov_b32_e32 v135, v137
	v_mov_b32_e32 v129, v137
	v_mov_b32_e32 v133, v137
	s_mov_b32 s9, 0
	v_lshl_add_u64 v[6:7], s[14:15], 0, v[130:131]
	global_load_lds_dwordx4 v132, s[4:5]
	v_lshl_add_u64 v[4:5], s[14:15], 0, v[134:135]
	v_lshl_add_u64 v[2:3], s[20:21], 0, v[128:129]
	s_cmp_lg_u32 s1, 1
	v_lshl_add_u64 v[0:1], s[20:21], 0, v[132:133]
	v_writelane_b32 v254, s5, 29
	s_cbranch_scc1 .LBB0_167
	s_barrier

; __device__ __forceinline__ unsigned xb_ld(unsigned* p)              { return __hip_atomic_load(p, __ATOMIC_RELAXED, __HIP_MEMORY_SCOPE_AGENT); }
; __device__ __forceinline__ unsigned xb_add(unsigned* p, unsigned v) { return __hip_atomic_fetch_add(p, v, __ATOMIC_RELAXED, __HIP_MEMORY_SCOPE_AGENT); }
; __device__ __forceinline__ void xcd_barrier_complete(unsigned* bar, unsigned x, unsigned& nloc, unsigned& nx) {
;     const unsigned G = gridDim.x * gridDim.y * gridDim.z;
;     unsigned sum, cnt, mine, sp = 0u;
;     for (;;) {
;         sum = 0u; cnt = 0u; mine = 0u;
; #pragma unroll
;         for (unsigned j = 0; j < 16; ++j) { const unsigned c = xb_ld(&bar[XB_XCNT(j)]); sum += c; cnt += (c > 0u) ? 1u : 0u; mine = (j == x) ? c : mine; }
;         if (sum == G) break;
;         __builtin_amdgcn_s_sleep(1);
;         if ((++sp & 255u) == 0u) { if (xb_ld(&bar[XB_TMO])) break; if (sp > XB_SPIN_CAP) { atomicAdd(&bar[XB_TMO], 1u); break; } }
;     }
;     nloc = mine > 0u ? mine : 1u; nx = cnt > 0u ? cnt : 1u;
; }
; __device__ __forceinline__ void xcd_barrier(const XcdBarrier& b) {
;     asm volatile("s_waitcnt vmcnt(0)" ::: "memory");
;     __syncthreads();
;     if (threadIdx.x == 0) {
;         unsigned* bar = b.bar;
;         __builtin_amdgcn_s_waitcnt(0);
;         unsigned nloc = b.st[0], nx = b.st[1];
;         if (nloc == 0u) { xcd_barrier_complete(bar, b.x, nloc, nx); b.st[0] = nloc; b.st[1] = nx; }
;         const unsigned old = xb_add(&bar[XB_XSUB(b.x)], 1u);
;         const unsigned gen = old / nloc;
;         if (old + 1u == (gen + 1u) * nloc) {
;             __builtin_amdgcn_fence(__ATOMIC_RELEASE, "agent");
;             asm volatile("s_waitcnt vmcnt(0)" ::: "memory");
;             const unsigned og = xb_add(&bar[XB_TOP], 1u);
;             const unsigned tg = og / nx;
;             if (og + 1u == (tg + 1u) * nx) xb_add(&bar[XB_TOPGEN], 1u);
.LBB0_489:
	s_or_b64 exec, exec, s[8:9]
	v_cvt_f32_u32_e32 v4, v2
	s_waitcnt vmcnt(0)
	v_readfirstlane_b32 s3, v3
	v_sub_u32_e32 v3, 0, v2
	v_rcp_iflag_f32_e32 v4, v4
	v_add_u32_e32 v5, s3, v1
	v_mul_f32_e32 v4, 0x4f7ffffe, v4
	v_cvt_u32_f32_e32 v4, v4
	v_mul_lo_u32 v1, v3, v4
	v_mul_hi_u32 v1, v4, v1
	v_add_u32_e32 v1, v4, v1
	v_mul_hi_u32 v1, v5, v1
	v_mul_lo_u32 v3, v1, v2
	v_sub_u32_e32 v3, v5, v3
	v_add_u32_e32 v4, 1, v1
	v_cmp_ge_u32_e32 vcc, v3, v2
	s_nop 1
	v_cndmask_b32_e32 v1, v1, v4, vcc
	v_sub_u32_e32 v4, v3, v2
	v_cndmask_b32_e32 v3, v3, v4, vcc
	v_add_u32_e32 v4, 1, v1
	v_cmp_ge_u32_e32 vcc, v3, v2
	v_add_u32_e32 v3, 1, v5
	s_nop 0
	v_cndmask_b32_e32 v1, v1, v4, vcc
	v_mul_lo_u32 v4, v2, v1
	v_add_u32_e32 v2, v4, v2
	v_cmp_ne_u32_e32 vcc, v3, v2
	s_and_saveexec_b64 s[6:7], vcc
	s_xor_b64 s[6:7], exec, s[6:7]
	s_cbranch_execz .LBB0_503
.LBB0_503:
	s_andn2_saveexec_b64 s[6:7], s[6:7]
	s_cbranch_execz .LBB0_523
	s_mov_b64 s[6:7], exec
	buffer_wbl2 sc1
	s_waitcnt lgkmcnt(0)
	s_waitcnt vmcnt(0)
	v_mbcnt_lo_u32_b32 v1, s6, 0
	v_mbcnt_hi_u32_b32 v1, s7, v1
	v_cmp_eq_u32_e32 vcc, 0, v1
	s_and_saveexec_b64 s[8:9], vcc
	s_cbranch_execz .LBB0_506
	s_bcnt1_i32_b64 s3, s[6:7]
	v_mov_b32_e32 v2, 0xff83000
	v_mov_b32_e32 v3, s3
	global_atomic_add v2, v2, v3, s[70:71] offset:1024 sc0

; __device__ __forceinline__ void run_phase(const Params& p, LAS unsigned char* lds, int ph) {
;     ...
;     case 4: {
;         const int c4 = blockIdx.x, pmt = (c4 & 7) * 8 + (c4 >> 5), j = (c4 >> 3) & 3;
;         unsigned* flags = (unsigned*)(p.ws + OFF_PFLAG);
;         if (j < 2) {
;             Sched64 S{c4, 2}; EpiPool E{p.ws, p.pool_scale};
.LBB0_523:
	s_or_b64 exec, exec, s[0:1]
	s_add_u32 s3, s70, 0xff88000
	v_cndmask_b32_e64 v1, 0, 1, s[42:43]
	s_waitcnt lgkmcnt(0)
	v_mov_b32_e32 v0, v224
	s_addc_u32 s27, s71, 0
	v_cmp_ne_u32_e64 s[8:9], 1, v1
	s_andn2_b64 vcc, exec, s[42:43]
	s_cbranch_vccnz .Lzp_early
	v_cmp_eq_u32_e32 vcc, 0, v224
	s_and_saveexec_b64 s[48:49], vcc
	s_cbranch_execz .Lgb3_done
	s_add_u32 s44, s70, 0xff83500
	s_addc_u32 s45, s71, 0
	s_mov_b32 s46, 0x8000
	v_mov_b32_e32 v250, 0
.Lgb3_spin:
	global_load_dword v251, v250, s[44:45] sc1
	s_waitcnt vmcnt(0)
	v_readfirstlane_b32 s47, v251
	s_cmp_ge_u32 s47, 3
	s_cbranch_scc1 .Lgb3_ok
	s_sleep 1
	s_sub_u32 s46, s46, 1
	s_cmp_lg_u32 s46, 0
	s_cbranch_scc1 .Lgb3_spin

; __device__ __forceinline__ int opaque_tid() { int t = (int)threadIdx.x; asm volatile("" : "+v"(t)); return t; }
; #define PG8_STAGE(bufoff, gbase, voff) do { _Pragma("unroll") for (int _i = 0; _i < 2; ++_i) \
;         __builtin_amdgcn_global_load_lds((const unsigned*)((const char*)(gbase) + (voff)[_i]), (LAS unsigned*)(lds + (bufoff) + ldsw + _i * 8192), 16, 0, 0); } while (0)
; #define PG8_WAIT_V(n) asm volatile("s_waitcnt vmcnt(" #n ")" ::: "memory")
; #define PG8_BAR __builtin_amdgcn_s_barrier()
; template <class Epi, class Sched, bool ZERO>
; __device__ __forceinline__ void gemm_phase_acc(LAS unsigned char* lds, const Gemm g, const Sched& S, const Epi& E, f32x4 (&acc)[2][2][4][2]) {
;     const int tid = opaque_tid(), wid = __builtin_amdgcn_readfirstlane(tid >> 6), lane = tid & 63, wr = wid >> 2, wc = wid & 3, fr = lane & 15, fq = lane >> 4;
;     const int K = g.K, nt = K / BK;
;     unsigned voffA[2], voffB[2];
; #pragma unroll
;     for (int i = 0; i < 2; ++i) { int R, C; stage_rc(tid * 16 + i * 8192, R, C); const int Rb = (R & ~31) + perm32(R & 31);
;         voffA[i] = (unsigned)(R * K + C) * 2u; voffB[i] = (unsigned)(Rb * K + C) * 2u; }
;     const size_t kstep = (size_t)(BK * 2);
;     const size_t hstep = (size_t)HALF * K * 2;
;     const size_t tstep = 2 * hstep;
;     const unsigned ldsw = (unsigned)wid * 1024u;
;     const int aoff = lds_byte(wr * 64 + fr, fq * 8), boff = lds_byte(wc * 32 + fr, fq * 8);
;     ...
;     Unit cur, nxt; int ui = 0;
;     if (!S.next(0, cur)) return;
;     if constexpr (ZERO) {
; #pragma unroll
;     for (int a = 0; a < 2; ++a)
; #pragma unroll
;         for (int b = 0; b < 2; ++b)
; #pragma unroll
;             for (int m = 0; m < 4; ++m)
; #pragma unroll
;                 for (int n = 0; n < 2; ++n) acc[a][b][m][n] = (f32x4){0.f, 0.f, 0.f, 0.f};
;     }
;     bf16x8 At[4][2], B0[2][2], B1[2][2];
;     const char* cA = (const char*)g.A + (size_t)cur.pm * tstep; const char* cB = (const char*)g.Bt + (size_t)cur.pn * tstep;
;     PG8_STAGE(PG8_SB(0, 0), cB, voffB); PG8_STAGE(PG8_SA(0, 0), cA, voffA); PG8_STAGE(PG8_SB(0, 1), cB + hstep, voffB); PG8_STAGE(PG8_SA(0, 1), cA + hstep, voffA);
;     if (wr == 1) PG8_BAR;
;     PG8_WAIT_V(4); PG8_BAR;
;     PG8_STAGE(PG8_SB(1, 0), cB + kstep, voffB); PG8_STAGE(PG8_SA(1, 0), cA + kstep, voffA); PG8_STAGE(PG8_SB(1, 1), cB + hstep + kstep, voffB);
;     PG8_WAIT_V(6); PG8_BAR;
.Lgb3_done:
	s_or_b64 exec, exec, s[48:49]
	s_barrier
	v_mov_b32_e32 v11, v224
	s_mov_b32 s0, 0x3fffe0
	v_lshlrev_b32_e32 v0, 4, v11
	v_add_u32_e32 v1, 0x2000, v0
	v_ashrrev_i32_e32 v2, 31, v1
	v_lshrrev_b32_e32 v2, 22, v2
	v_add_u32_e32 v2, v1, v2
	v_ashrrev_i32_e32 v8, 10, v2
	v_mul_i32_i24_e32 v2, 0x400, v8
	v_sub_u32_e32 v1, v1, v2
	v_lshrrev_b32_e32 v2, 4, v1
	v_bitop3_b32 v1, v2, v1, 32 bitop3:0x6c
	v_ashrrev_i32_e32 v2, 31, v1
	v_lshrrev_b32_e32 v2, 26, v2
	v_add_u32_e32 v2, v1, v2
	v_lshlrev_b32_e32 v3, 3, v8
	v_ashrrev_i32_e32 v9, 6, v2
	v_and_b32_e32 v3, -16, v3
	v_add_u32_e32 v3, v9, v3
	v_and_b32_e32 v4, 3, v9
	v_lshrrev_b32_e32 v5, 2, v3
	v_lshlrev_b32_e32 v6, 1, v3
	v_and_b32_e32 v2, 0xc0, v2
	v_and_or_b32 v4, v3, s0, v4
	v_and_b32_e32 v5, 4, v5
	v_and_b32_e32 v6, 24, v6
	v_sub_u32_e32 v1, v1, v2
	v_mov_b32_e32 v2, 1
	v_or3_b32 v4, v4, v5, v6
	v_lshlrev_b32_e32 v5, 5, v8
	v_ashrrev_i16_sdwa v1, v2, sext(v1) dst_sel:DWORD dst_unused:UNUSED_PAD src0_sel:DWORD src1_sel:BYTE_0
	v_and_b32_e32 v5, 32, v5
	v_bfe_i32 v10, v1, 0, 16
	v_add_lshl_u32 v1, v5, v10, 1
	v_lshl_add_u32 v128, v4, 10, v1
	v_lshl_add_u32 v130, v3, 10, v1
	v_bfe_i32 v1, v11, 27, 1
	v_lshrrev_b32_e32 v1, 22, v1
	v_add_u32_e32 v1, v0, v1
	v_and_b32_e32 v1, 0xfffffc00, v1
	v_sub_u32_e32 v0, v0, v1
	v_lshrrev_b32_e32 v1, 4, v0
	v_bitop3_b32 v1, v1, v0, 32 bitop3:0x6c
	v_ashrrev_i32_e32 v0, 31, v0
	v_lshrrev_b32_e32 v0, 26, v0
	v_add_u32_e32 v0, v1, v0
	v_ashrrev_i32_e32 v12, 6, v0
	v_ashrrev_i32_e32 v0, 31, v11
	v_lshrrev_b32_e32 v0, 26, v0
	v_add_u32_e32 v0, v11, v0
	v_ashrrev_i32_e32 v13, 6, v0
	v_lshlrev_b32_e32 v0, 3, v13
	v_and_b32_e32 v0, -16, v0
	v_add_u32_e32 v0, v12, v0
	v_readfirstlane_b32 s24, v11
	v_and_b32_e32 v3, 3, v12
	v_lshrrev_b32_e32 v4, 2, v0
	v_lshlrev_b32_e32 v5, 1, v0
	s_ashr_i32 s6, s24, 6
	v_and_or_b32 v3, v0, s0, v3
	v_and_b32_e32 v4, 4, v4
	v_and_b32_e32 v5, 24, v5
	s_ashr_i32 s7, s24, 8
	s_lshl_b32 s44, s6, 10
	v_or3_b32 v3, v3, v4, v5
	v_mul_i32_i24_e32 v5, 64, v12
	s_lshl_b64 s[10:11], s[18:19], 18
	s_lshl_b32 s42, s34, 18
	v_sub_u32_e32 v1, v1, v5
	s_add_u32 s28, s70, s42
	v_lshlrev_b32_e32 v4, 5, v13
	v_ashrrev_i16_sdwa v1, v2, sext(v1) dst_sel:DWORD dst_unused:UNUSED_PAD src0_sel:DWORD src1_sel:BYTE_0
	s_addc_u32 s29, s71, 0
	v_and_b32_e32 v4, 32, v4
	v_bfe_i32 v14, v1, 0, 16
	s_add_u32 s0, s28, 0x2000000
	v_add_lshl_u32 v1, v4, v14, 1
	s_addc_u32 s1, s29, 0
	s_add_i32 s25, s44, 0
	v_lshl_add_u32 v132, v3, 10, v1
	s_add_i32 m0, s25, 0x10000
	v_lshl_add_u32 v134, v0, 10, v1
	global_load_lds_dwordx4 v132, s[0:1]
	s_add_i32 m0, s25, 0x12000
	s_add_u32 s4, s41, s10
	global_load_lds_dwordx4 v128, s[0:1]
	s_addc_u32 s5, s94, s11
	s_mov_b32 m0, s25
	s_add_i32 s26, s25, 0x2000
	global_load_lds_dwordx4 v134, s[4:5]
	s_mov_b32 m0, s26
	s_add_u32 s28, s28, 0x2020000
	global_load_lds_dwordx4 v130, s[4:5]
	s_addc_u32 s29, s29, 0
	s_add_i32 m0, s25, 0x14000
	v_mov_b32_e32 v133, 0
	global_load_lds_dwordx4 v132, s[28:29]
	s_add_i32 m0, s25, 0x16000
	s_add_u32 s38, s4, 0x20000
	global_load_lds_dwordx4 v128, s[28:29]
	s_addc_u32 s39, s5, 0
	s_add_i32 s28, s25, 0x4000
	s_mov_b32 m0, s28
	s_add_i32 s29, s25, 0x6000
	global_load_lds_dwordx4 v134, s[38:39]
	s_mov_b32 m0, s29
	v_mov_b32_e32 v129, v133
	global_load_lds_dwordx4 v130, s[38:39]
	v_mov_b32_e32 v135, v133
	v_mov_b32_e32 v131, v133
	v_lshl_add_u64 v[6:7], s[0:1], 0, v[132:133]
	v_lshl_add_u64 v[4:5], s[0:1], 0, v[128:129]
	v_lshl_add_u64 v[2:3], s[4:5], 0, v[134:135]
	s_cmp_lg_u32 s7, 1
	v_lshl_add_u64 v[0:1], s[4:5], 0, v[130:131]
	s_cbranch_scc1 .LBB0_526
	s_barrier

; #define PG8_WAIT_V(n) asm volatile("s_waitcnt vmcnt(" #n ")" ::: "memory")
; template <class Epi, class Sched, bool ZERO>
; __device__ __forceinline__ void gemm_phase_acc(LAS unsigned char* lds, const Gemm g, const Sched& S, const Epi& E, f32x4 (&acc)[2][2][4][2]) {
;     const int tid = opaque_tid(), wid = __builtin_amdgcn_readfirstlane(tid >> 6), lane = tid & 63, wr = wid >> 2, wc = wid & 3, fr = lane & 15, fq = lane >> 4;
;     const int K = g.K, nt = K / BK;
;     unsigned voffA[2], voffB[2];
; #pragma unroll
;     for (int i = 0; i < 2; ++i) { int R, C; stage_rc(tid * 16 + i * 8192, R, C); const int Rb = (R & ~31) + perm32(R & 31);
;         voffA[i] = (unsigned)(R * K + C) * 2u; voffB[i] = (unsigned)(Rb * K + C) * 2u; }
;     const size_t kstep = (size_t)(BK * 2);
;     const size_t hstep = (size_t)HALF * K * 2;
;     const size_t tstep = 2 * hstep;
;     const unsigned ldsw = (unsigned)wid * 1024u;
;     const int aoff = lds_byte(wr * 64 + fr, fq * 8), boff = lds_byte(wc * 32 + fr, fq * 8);
;     ...
;     Unit cur, nxt; int ui = 0;
;     if (!S.next(0, cur)) return;
;     if constexpr (ZERO) {
; #pragma unroll
;     for (int a = 0; a < 2; ++a)
; #pragma unroll
;         for (int b = 0; b < 2; ++b)
; #pragma unroll
;             for (int m = 0; m < 4; ++m)
; #pragma unroll
;                 for (int n = 0; n < 2; ++n) acc[a][b][m][n] = (f32x4){0.f, 0.f, 0.f, 0.f};
;     }
;     bf16x8 At[4][2], B0[2][2], B1[2][2];
;     const char* cA = (const char*)g.A + (size_t)cur.pm * tstep; const char* cB = (const char*)g.Bt + (size_t)cur.pn * tstep;
;     PG8_STAGE(PG8_SB(0, 0), cB, voffB); PG8_STAGE(PG8_SA(0, 0), cA, voffA); PG8_STAGE(PG8_SB(0, 1), cB + hstep, voffB); PG8_STAGE(PG8_SA(0, 1), cA + hstep, voffA);
;     if (wr == 1) PG8_BAR;
;     PG8_WAIT_V(4); PG8_BAR;
;     PG8_STAGE(PG8_SB(1, 0), cB + kstep, voffB); PG8_STAGE(PG8_SA(1, 0), cA + kstep, voffA); PG8_STAGE(PG8_SB(1, 1), cB + hstep + kstep, voffB);
;     PG8_WAIT_V(6); PG8_BAR;
; __device__ __forceinline__ void run_phase(const Params& p, LAS unsigned char* lds, int ph) {
;     ...
;         if (j >= 2) {
;             if (threadIdx.x < 64) { unsigned spins = 0;
;                 while ((unsigned)__builtin_amdgcn_readfirstlane(__hip_atomic_load(flags + 64 * (pmt * 2 + j - 2), __ATOMIC_RELAXED, __HIP_MEMORY_SCOPE_AGENT)) == 0u) { __builtin_amdgcn_s_sleep(2); if (++spins > (1u << 22)) break; }
.LBB0_617:
	s_branch .LBB0_672
.Lzp_early:
	v_readlane_b32 s56, v254, 28
	v_readlane_b32 s57, v254, 29
	v_writelane_b32 v254, s2, 40
	v_writelane_b32 v254, s3, 41
	v_writelane_b32 v254, s8, 42
	v_writelane_b32 v254, s9, 43
	v_writelane_b32 v254, s14, 44
	v_writelane_b32 v254, s15, 45
	v_writelane_b32 v254, s16, 46
	v_writelane_b32 v254, s17, 47
	v_writelane_b32 v254, s27, 48
	v_writelane_b32 v254, s30, 49
	v_writelane_b32 v254, s31, 50
	v_writelane_b32 v254, s38, 51
	v_writelane_b32 v254, s39, 52
	v_mov_b32_e32 v13, v224
	s_barrier
	s_mov_b32 s0, 0x1fffe0
	v_ashrrev_i32_e32 v1, 31, v13
	v_lshrrev_b32_e32 v1, 26, v1
	v_add_u32_e32 v1, v13, v1
	v_ashrrev_i32_e32 v8, 6, v1
	v_bfe_i32 v1, v13, 27, 1
	v_lshlrev_b32_e32 v0, 4, v13
	v_lshrrev_b32_e32 v1, 22, v1
	v_add_u32_e32 v1, v0, v1
	v_and_b32_e32 v1, 0xfffffc00, v1
	v_sub_u32_e32 v1, v0, v1
	v_lshrrev_b32_e32 v2, 4, v1
	v_bitop3_b32 v2, v2, v1, 32 bitop3:0x6c
	v_ashrrev_i32_e32 v1, 31, v1
	v_lshrrev_b32_e32 v1, 26, v1
	v_add_u32_e32 v1, v2, v1
	v_ashrrev_i32_e32 v9, 6, v1
	v_lshlrev_b32_e32 v3, 3, v8
	v_mul_i32_i24_e32 v4, 64, v9
	v_and_b32_e32 v3, -16, v3
	v_sub_u32_e32 v2, v2, v4
	v_mov_b32_e32 v4, 1
	v_add_u32_e32 v1, v9, v3
	v_lshlrev_b32_e32 v3, 5, v8
	v_ashrrev_i16_sdwa v2, v4, sext(v2) dst_sel:DWORD dst_unused:UNUSED_PAD src0_sel:DWORD src1_sel:BYTE_0
	v_and_b32_e32 v3, 32, v3
	v_bfe_i32 v10, v2, 0, 16
	v_and_b32_e32 v6, 3, v9
	v_add_lshl_u32 v3, v3, v10, 1
	v_add_u32_e32 v0, 0x2000, v0
	v_lshlrev_b32_e32 v2, 1, v1
	v_lshrrev_b32_e32 v5, 2, v1
	v_and_or_b32 v6, v1, s0, v6
	v_lshl_add_u32 v48, v1, 11, v3
	v_ashrrev_i32_e32 v1, 31, v0
	v_lshrrev_b32_e32 v1, 22, v1
	v_add_u32_e32 v1, v0, v1
	v_ashrrev_i32_e32 v11, 10, v1
	v_mul_i32_i24_e32 v1, 0x400, v11
	v_sub_u32_e32 v0, v0, v1
	v_and_b32_e32 v2, 24, v2
	v_and_b32_e32 v5, 4, v5
	v_lshrrev_b32_e32 v1, 4, v0
	v_or3_b32 v2, v6, v5, v2
	v_bitop3_b32 v0, v1, v0, 32 bitop3:0x6c
	v_lshl_add_u32 v50, v2, 11, v3
	v_ashrrev_i32_e32 v2, 31, v0
	v_lshrrev_b32_e32 v2, 26, v2
	v_add_u32_e32 v2, v0, v2
	v_lshlrev_b32_e32 v1, 3, v11
	v_ashrrev_i32_e32 v12, 6, v2
	v_and_b32_e32 v2, 0xc0, v2
	v_and_b32_e32 v1, -16, v1
	v_sub_u32_e32 v0, v0, v2
	v_readfirstlane_b32 s10, v13
	v_add_u32_e32 v1, v12, v1
	v_ashrrev_i16_sdwa v0, v4, sext(v0) dst_sel:DWORD dst_unused:UNUSED_PAD src0_sel:DWORD src1_sel:BYTE_0
	v_and_b32_e32 v4, 3, v12
	s_ashr_i32 s3, s10, 6
	v_and_or_b32 v4, v1, s0, v4
	v_readlane_b32 s0, v254, 30
	s_ashr_i32 s4, s10, 8
	s_lshl_b32 s6, s3, 10
	s_lshl_b32 s0, s0, 19
	v_lshlrev_b32_e32 v3, 5, v11
	v_bfe_i32 v14, v0, 0, 16
	v_lshlrev_b32_e32 v0, 1, v1
	v_lshrrev_b32_e32 v2, 2, v1
	s_add_u32 s0, s70, s0
	v_and_b32_e32 v3, 32, v3
	v_and_b32_e32 v0, 24, v0
	v_and_b32_e32 v2, 4, v2
	s_addc_u32 s1, s71, 0
	s_add_i32 s11, s6, 0
	v_or3_b32 v0, v4, v2, v0
	v_add_lshl_u32 v2, v3, v14, 1
	s_add_i32 m0, s11, 0x10000
	v_lshl_add_u32 v62, v0, 11, v2
	global_load_lds_dwordx4 v50, s[0:1]
	s_add_i32 m0, s11, 0x12000
	s_add_i32 s14, s11, 0x2000
	global_load_lds_dwordx4 v62, s[0:1]
	s_mov_b32 m0, s11
	v_lshl_add_u32 v60, v1, 11, v2
	global_load_lds_dwordx4 v48, s[20:21]
	s_mov_b32 m0, s14
	s_add_u32 s8, s0, 0x40000
	global_load_lds_dwordx4 v60, s[20:21]
	s_addc_u32 s9, s1, 0
	s_add_i32 m0, s11, 0x14000
	s_add_i32 s15, s11, 0x4000
	global_load_lds_dwordx4 v50, s[8:9]
	s_add_i32 m0, s11, 0x16000
	s_add_i32 s16, s11, 0x6000
	global_load_lds_dwordx4 v62, s[8:9]
	s_mov_b32 m0, s15
	v_mov_b32_e32 v51, 0
	global_load_lds_dwordx4 v48, s[56:57]
	s_mov_b32 m0, s16
	v_mov_b32_e32 v63, v51
	global_load_lds_dwordx4 v60, s[56:57]
	v_mov_b32_e32 v49, v51
	v_mov_b32_e32 v61, v51
	v_lshl_add_u64 v[6:7], s[0:1], 0, v[50:51]
	v_lshl_add_u64 v[4:5], s[0:1], 0, v[62:63]
	v_lshl_add_u64 v[2:3], s[20:21], 0, v[48:49]
	s_cmp_lg_u32 s4, 1
	v_lshl_add_u64 v[0:1], s[20:21], 0, v[60:61]
	s_cbranch_scc1 .LBB0_630
	s_barrier

; #define PG8_STAGE(bufoff, gbase, voff) do { _Pragma("unroll") for (int _i = 0; _i < 2; ++_i) \
;         __builtin_amdgcn_global_load_lds((const unsigned*)((const char*)(gbase) + (voff)[_i]), (LAS unsigned*)(lds + (bufoff) + ldsw + _i * 8192), 16, 0, 0); } while (0)
; #define PG8_LDA(dst, b, h) do { _Pragma("unroll") for (int m = 0; m < 4; ++m) _Pragma("unroll") for (int k = 0; k < 2; ++k) dst[m][k] = *(const LAS bf16x8*)(lds + PG8_SA(b, h) + aoff + m * 2048 + k * 1024); } while (0)
; #define PG8_LDB(dst, b, h) do { _Pragma("unroll") for (int n = 0; n < 2; ++n) _Pragma("unroll") for (int k = 0; k < 2; ++k) dst[n][k] = *(const LAS bf16x8*)(lds + PG8_SB(b, h) + boff + n * 2048 + k * 1024); } while (0)
; #define PG8_MMA(ai, bj, At, Bt) do { __builtin_amdgcn_s_setprio(1); _Pragma("unroll") for (int m = 0; m < 4; ++m) _Pragma("unroll") for (int n = 0; n < 2; ++n) _Pragma("unroll") for (int k = 0; k < 2; ++k) \
;         acc[ai][bj][m][n] = __builtin_amdgcn_mfma_f32_16x16x32_bf16(Bt[n][k], At[m][k], acc[ai][bj][m][n], 0, 0, 0); __builtin_amdgcn_s_setprio(0); } while (0)
; #define PG8_WAIT_L(n) asm volatile("s_waitcnt lgkmcnt(" #n ")" ::: "memory")
; #define PG8_BAR __builtin_amdgcn_s_barrier()
; #define PG8_SCHED __builtin_amdgcn_sched_barrier(0)
; template <class Epi, class Sched, bool ZERO>
; __device__ __forceinline__ void gemm_phase_acc(LAS unsigned char* lds, const Gemm g, const Sched& S, const Epi& E, f32x4 (&acc)[2][2][4][2]) {
;     ...
;             PG8_LDB(B0, 0, 0); PG8_SCHED; PG8_LDA(At, 0, 0); PG8_STAGE(PG8_SA(1, 1), a1 + hstep, voffA);
;             PG8_WAIT_L(8); PG8_BAR; PG8_WAIT_L(0); PG8_MMA(0, 0, At, B0); PG8_BAR; PG8_SCHED;
;             PG8_LDB(B1, 0, 1); PG8_STAGE(PG8_SB(0, 0), b2, voffB);
;             PG8_BAR; PG8_WAIT_L(0); PG8_MMA(0, 1, At, B1); PG8_BAR;
;             PG8_LDA(At, 0, 1); PG8_STAGE(PG8_SA(0, 0), a2, voffA);
;             PG8_BAR; PG8_WAIT_L(0); PG8_MMA(1, 0, At, B0); PG8_BAR; PG8_SCHED;
.LBB0_631:
	s_add_u32 s6, s20, s2
	ds_read_b128 v[100:103], v86
	ds_read_b128 v[112:115], v86 offset:1024
	ds_read_b128 v[124:127], v86 offset:2048
	ds_read_b128 v[160:163], v86 offset:3072
	s_addc_u32 s7, s21, s3
	s_add_u32 s6, s6, 0x100
	s_addc_u32 s7, s7, 0
	s_add_u32 s45, s26, s2
	s_addc_u32 s46, s27, s3
	s_cmpk_eq_i32 s2, 0x700
	s_cselect_b32 s9, s21, s7
	s_cselect_b32 s8, s20, s6
	s_cselect_b32 s7, s1, s46
	s_cselect_b32 s6, s0, s45
	s_mov_b32 m0, s29
	v_lshl_add_u64 v[196:197], v[72:73], 0, s[2:3]
	ds_read_b128 v[164:167], v87
	ds_read_b128 v[168:171], v87 offset:1024
	ds_read_b128 v[172:175], v87 offset:2048
	ds_read_b128 v[176:179], v87 offset:3072
	ds_read_b128 v[180:183], v87 offset:4096
	ds_read_b128 v[184:187], v87 offset:5120
	ds_read_b128 v[188:191], v87 offset:6144
	ds_read_b128 v[192:195], v87 offset:7168
	global_load_lds_dwordx4 v[196:197], off
	v_lshl_add_u64 v[196:197], v[74:75], 0, s[2:3]
	s_mov_b32 m0, s30
	s_nop 0
	global_load_lds_dwordx4 v[196:197], off
	s_waitcnt lgkmcnt(8)
	s_barrier
	s_waitcnt lgkmcnt(0)
	s_setprio 1
	s_waitcnt lgkmcnt(0)
	v_mfma_f32_16x16x32_bf16 v[156:159], v[100:103], v[164:167], v[156:159]
	v_mfma_f32_16x16x32_bf16 v[152:155], v[124:127], v[164:167], v[152:155]
	v_mfma_f32_16x16x32_bf16 v[140:143], v[100:103], v[172:175], v[140:143]
	v_mfma_f32_16x16x32_bf16 v[136:139], v[124:127], v[172:175], v[136:139]
	v_mfma_f32_16x16x32_bf16 v[120:123], v[100:103], v[180:183], v[120:123]
	v_mfma_f32_16x16x32_bf16 v[116:119], v[124:127], v[180:183], v[116:119]
	v_mfma_f32_16x16x32_bf16 v[96:99], v[100:103], v[188:191], v[96:99]
	v_mfma_f32_16x16x32_bf16 v[92:95], v[124:127], v[188:191], v[92:95]
	v_mfma_f32_16x16x32_bf16 v[156:159], v[112:115], v[168:171], v[156:159]
	v_mfma_f32_16x16x32_bf16 v[152:155], v[160:163], v[168:171], v[152:155]
	v_mfma_f32_16x16x32_bf16 v[140:143], v[112:115], v[176:179], v[140:143]
	v_mfma_f32_16x16x32_bf16 v[136:139], v[160:163], v[176:179], v[136:139]
	v_mfma_f32_16x16x32_bf16 v[120:123], v[112:115], v[184:187], v[120:123]
	v_mfma_f32_16x16x32_bf16 v[116:119], v[160:163], v[184:187], v[116:119]
	v_mfma_f32_16x16x32_bf16 v[96:99], v[112:115], v[192:195], v[96:99]
	v_mfma_f32_16x16x32_bf16 v[92:95], v[160:163], v[192:195], v[92:95]
	s_setprio 0
	s_barrier
	s_mov_b32 m0, s31
	v_lshl_add_u64 v[212:213], s[6:7], 0, v[50:51]
	ds_read_b128 v[196:199], v88
	ds_read_b128 v[200:203], v88 offset:1024
	ds_read_b128 v[204:207], v88 offset:2048
	ds_read_b128 v[208:211], v88 offset:3072
	global_load_lds_dwordx4 v[212:213], off
	v_lshl_add_u64 v[214:215], s[6:7], 0, v[62:63]
	s_mov_b32 m0, s38
	s_nop 0
	global_load_lds_dwordx4 v[214:215], off
	s_barrier
	s_waitcnt lgkmcnt(0)
	s_setprio 1
	s_waitcnt lgkmcnt(0)
	v_mfma_f32_16x16x32_bf16 v[148:151], v[196:199], v[164:167], v[148:151]
	v_mfma_f32_16x16x32_bf16 v[144:147], v[204:207], v[164:167], v[144:147]
	v_mfma_f32_16x16x32_bf16 v[132:135], v[196:199], v[172:175], v[132:135]
	v_mfma_f32_16x16x32_bf16 v[128:131], v[204:207], v[172:175], v[128:131]
	v_mfma_f32_16x16x32_bf16 v[108:111], v[196:199], v[180:183], v[108:111]
	v_mfma_f32_16x16x32_bf16 v[104:107], v[204:207], v[180:183], v[104:107]
	v_mfma_f32_16x16x32_bf16 v[80:83], v[196:199], v[188:191], v[80:83]
	v_mfma_f32_16x16x32_bf16 v[76:79], v[204:207], v[188:191], v[76:79]
	v_mfma_f32_16x16x32_bf16 v[148:151], v[200:203], v[168:171], v[148:151]
	v_mfma_f32_16x16x32_bf16 v[144:147], v[208:211], v[168:171], v[144:147]
	v_mfma_f32_16x16x32_bf16 v[132:135], v[200:203], v[176:179], v[132:135]
	v_mfma_f32_16x16x32_bf16 v[128:131], v[208:211], v[176:179], v[128:131]
	v_mfma_f32_16x16x32_bf16 v[108:111], v[200:203], v[184:187], v[108:111]
	v_mfma_f32_16x16x32_bf16 v[104:107], v[208:211], v[184:187], v[104:107]
	v_mfma_f32_16x16x32_bf16 v[80:83], v[200:203], v[192:195], v[80:83]
	v_mfma_f32_16x16x32_bf16 v[76:79], v[208:211], v[192:195], v[76:79]
	s_setprio 0
	s_mov_b32 m0, s11
	v_lshl_add_u64 v[216:217], s[8:9], 0, v[48:49]
	s_barrier
	ds_read_b128 v[164:167], v87 offset:16384
	ds_read_b128 v[168:171], v87 offset:17408
	ds_read_b128 v[172:175], v87 offset:18432
	ds_read_b128 v[176:179], v87 offset:19456
	ds_read_b128 v[180:183], v87 offset:20480
	ds_read_b128 v[184:187], v87 offset:21504
	ds_read_b128 v[188:191], v87 offset:22528
	ds_read_b128 v[192:195], v87 offset:23552
	global_load_lds_dwordx4 v[216:217], off
	v_lshl_add_u64 v[218:219], s[8:9], 0, v[60:61]
	s_mov_b32 m0, s14
	s_nop 0
	global_load_lds_dwordx4 v[218:219], off
	s_barrier
	s_waitcnt lgkmcnt(0)
	s_setprio 1
	s_waitcnt lgkmcnt(0)
	v_mfma_f32_16x16x32_bf16 v[68:71], v[100:103], v[164:167], v[68:71]
	v_mfma_f32_16x16x32_bf16 v[64:67], v[124:127], v[164:167], v[64:67]
	v_mfma_f32_16x16x32_bf16 v[44:47], v[100:103], v[172:175], v[44:47]
	v_mfma_f32_16x16x32_bf16 v[40:43], v[124:127], v[172:175], v[40:43]
	v_mfma_f32_16x16x32_bf16 v[28:31], v[100:103], v[180:183], v[28:31]
	v_mfma_f32_16x16x32_bf16 v[24:27], v[124:127], v[180:183], v[24:27]
	v_mfma_f32_16x16x32_bf16 v[12:15], v[100:103], v[188:191], v[12:15]
	v_mfma_f32_16x16x32_bf16 v[8:11], v[124:127], v[188:191], v[8:11]
	v_mfma_f32_16x16x32_bf16 v[68:71], v[112:115], v[168:171], v[68:71]
	v_mfma_f32_16x16x32_bf16 v[64:67], v[160:163], v[168:171], v[64:67]
	v_mfma_f32_16x16x32_bf16 v[44:47], v[112:115], v[176:179], v[44:47]
	v_mfma_f32_16x16x32_bf16 v[40:43], v[160:163], v[176:179], v[40:43]
	v_mfma_f32_16x16x32_bf16 v[28:31], v[112:115], v[184:187], v[28:31]
	v_mfma_f32_16x16x32_bf16 v[24:27], v[160:163], v[184:187], v[24:27]
	v_mfma_f32_16x16x32_bf16 v[12:15], v[112:115], v[192:195], v[12:15]
	v_mfma_f32_16x16x32_bf16 v[8:11], v[160:163], v[192:195], v[8:11]
	s_setprio 0
	s_barrier
; #define PG8_STAGE(bufoff, gbase, voff) do { _Pragma("unroll") for (int _i = 0; _i < 2; ++_i) \
;         __builtin_amdgcn_global_load_lds((const unsigned*)((const char*)(gbase) + (voff)[_i]), (LAS unsigned*)(lds + (bufoff) + ldsw + _i * 8192), 16, 0, 0); } while (0)
; #define PG8_LDA(dst, b, h) do { _Pragma("unroll") for (int m = 0; m < 4; ++m) _Pragma("unroll") for (int k = 0; k < 2; ++k) dst[m][k] = *(const LAS bf16x8*)(lds + PG8_SA(b, h) + aoff + m * 2048 + k * 1024); } while (0)
; #define PG8_LDB(dst, b, h) do { _Pragma("unroll") for (int n = 0; n < 2; ++n) _Pragma("unroll") for (int k = 0; k < 2; ++k) dst[n][k] = *(const LAS bf16x8*)(lds + PG8_SB(b, h) + boff + n * 2048 + k * 1024); } while (0)
; #define PG8_MMA(ai, bj, At, Bt) do { __builtin_amdgcn_s_setprio(1); _Pragma("unroll") for (int m = 0; m < 4; ++m) _Pragma("unroll") for (int n = 0; n < 2; ++n) _Pragma("unroll") for (int k = 0; k < 2; ++k) \
;         acc[ai][bj][m][n] = __builtin_amdgcn_mfma_f32_16x16x32_bf16(Bt[n][k], At[m][k], acc[ai][bj][m][n], 0, 0, 0); __builtin_amdgcn_s_setprio(0); } while (0)
; #define PG8_WAIT_V(n) asm volatile("s_waitcnt vmcnt(" #n ")" ::: "memory")
; #define PG8_WAIT_L(n) asm volatile("s_waitcnt lgkmcnt(" #n ")" ::: "memory")
; #define PG8_BAR __builtin_amdgcn_s_barrier()
; #define PG8_SCHED __builtin_amdgcn_sched_barrier(0)
; template <class Epi, class Sched, bool ZERO>
; __device__ __forceinline__ void gemm_phase_acc(LAS unsigned char* lds, const Gemm g, const Sched& S, const Epi& E, f32x4 (&acc)[2][2][4][2]) {
;     ...
;             PG8_STAGE(PG8_SB(0, 1), b2 + hstep, voffB);
;             PG8_WAIT_V(6); PG8_BAR; PG8_MMA(1, 1, At, B1); PG8_BAR;
;             PG8_LDB(B0, 1, 0); PG8_SCHED; PG8_LDA(At, 1, 0); PG8_STAGE(PG8_SA(0, 1), a2 + hstep, voffA);
;             PG8_WAIT_L(8); PG8_BAR; PG8_WAIT_L(0); PG8_MMA(0, 0, At, B0); PG8_BAR; PG8_SCHED;
;             PG8_LDB(B1, 1, 1); PG8_STAGE(PG8_SB(1, 0), b3, voffB);
;             PG8_BAR; PG8_WAIT_L(0); PG8_MMA(0, 1, At, B1); PG8_BAR;
	s_add_u32 s46, s6, 0x40000
	s_addc_u32 s47, s7, 0
	s_mov_b32 m0, s39
	v_lshl_add_u64 v[100:101], s[46:47], 0, v[50:51]
	global_load_lds_dwordx4 v[100:101], off
	v_lshl_add_u64 v[100:101], s[46:47], 0, v[62:63]
	s_mov_b32 m0, s40
	s_nop 0
	global_load_lds_dwordx4 v[100:101], off
	s_waitcnt vmcnt(6)
	s_barrier
	s_setprio 1
	v_mfma_f32_16x16x32_bf16 v[56:59], v[196:199], v[164:167], v[56:59]
	v_mfma_f32_16x16x32_bf16 v[52:55], v[204:207], v[164:167], v[52:55]
	v_mfma_f32_16x16x32_bf16 v[36:39], v[196:199], v[172:175], v[36:39]
	v_mfma_f32_16x16x32_bf16 v[32:35], v[204:207], v[172:175], v[32:35]
	v_mfma_f32_16x16x32_bf16 v[20:23], v[196:199], v[180:183], v[20:23]
	v_mfma_f32_16x16x32_bf16 v[16:19], v[204:207], v[180:183], v[16:19]
	v_mfma_f32_16x16x32_bf16 v[4:7], v[196:199], v[188:191], v[4:7]
	v_mfma_f32_16x16x32_bf16 v[0:3], v[204:207], v[188:191], v[0:3]
	v_mfma_f32_16x16x32_bf16 v[56:59], v[200:203], v[168:171], v[56:59]
	v_mfma_f32_16x16x32_bf16 v[52:55], v[208:211], v[168:171], v[52:55]
	v_mfma_f32_16x16x32_bf16 v[36:39], v[200:203], v[176:179], v[36:39]
	v_mfma_f32_16x16x32_bf16 v[32:35], v[208:211], v[176:179], v[32:35]
	v_mfma_f32_16x16x32_bf16 v[20:23], v[200:203], v[184:187], v[20:23]
	v_mfma_f32_16x16x32_bf16 v[16:19], v[208:211], v[184:187], v[16:19]
	v_mfma_f32_16x16x32_bf16 v[4:7], v[200:203], v[192:195], v[4:7]
	v_mfma_f32_16x16x32_bf16 v[0:3], v[208:211], v[192:195], v[0:3]
	s_setprio 0
	s_barrier
	ds_read_b128 v[100:103], v89
	ds_read_b128 v[112:115], v89 offset:1024
	ds_read_b128 v[124:127], v89 offset:2048
	ds_read_b128 v[160:163], v89 offset:3072
	s_add_u32 s8, s8, 0x40000
	s_addc_u32 s9, s9, 0
	s_mov_b32 m0, s15
	v_lshl_add_u64 v[196:197], s[8:9], 0, v[48:49]
	ds_read_b128 v[164:167], v87 offset:32768
	ds_read_b128 v[168:171], v87 offset:33792
	ds_read_b128 v[172:175], v87 offset:34816
	ds_read_b128 v[176:179], v87 offset:35840
	ds_read_b128 v[180:183], v87 offset:36864
	ds_read_b128 v[184:187], v87 offset:37888
	ds_read_b128 v[188:191], v87 offset:38912
	ds_read_b128 v[192:195], v87 offset:39936
	global_load_lds_dwordx4 v[196:197], off
	v_lshl_add_u64 v[196:197], s[8:9], 0, v[60:61]
	s_mov_b32 m0, s16
	s_nop 0
	global_load_lds_dwordx4 v[196:197], off
	s_waitcnt lgkmcnt(8)
	s_barrier
	s_waitcnt lgkmcnt(0)
	s_setprio 1
	s_waitcnt lgkmcnt(0)
	v_mfma_f32_16x16x32_bf16 v[156:159], v[100:103], v[164:167], v[156:159]
	v_mfma_f32_16x16x32_bf16 v[152:155], v[124:127], v[164:167], v[152:155]
	v_mfma_f32_16x16x32_bf16 v[140:143], v[100:103], v[172:175], v[140:143]
	v_mfma_f32_16x16x32_bf16 v[136:139], v[124:127], v[172:175], v[136:139]
	v_mfma_f32_16x16x32_bf16 v[120:123], v[100:103], v[180:183], v[120:123]
	v_mfma_f32_16x16x32_bf16 v[116:119], v[124:127], v[180:183], v[116:119]
	v_mfma_f32_16x16x32_bf16 v[96:99], v[100:103], v[188:191], v[96:99]
	v_mfma_f32_16x16x32_bf16 v[92:95], v[124:127], v[188:191], v[92:95]
	v_mfma_f32_16x16x32_bf16 v[156:159], v[112:115], v[168:171], v[156:159]
	v_mfma_f32_16x16x32_bf16 v[152:155], v[160:163], v[168:171], v[152:155]
	v_mfma_f32_16x16x32_bf16 v[140:143], v[112:115], v[176:179], v[140:143]
	v_mfma_f32_16x16x32_bf16 v[136:139], v[160:163], v[176:179], v[136:139]
	v_mfma_f32_16x16x32_bf16 v[120:123], v[112:115], v[184:187], v[120:123]
	v_mfma_f32_16x16x32_bf16 v[116:119], v[160:163], v[184:187], v[116:119]
	v_mfma_f32_16x16x32_bf16 v[96:99], v[112:115], v[192:195], v[96:99]
	v_mfma_f32_16x16x32_bf16 v[92:95], v[160:163], v[192:195], v[92:95]
	s_setprio 0
	s_barrier
	s_mov_b32 m0, s41
	v_lshl_add_u64 v[212:213], v[212:213], 0, s[4:5]
	ds_read_b128 v[196:199], v90
	ds_read_b128 v[200:203], v90 offset:1024
	ds_read_b128 v[204:207], v90 offset:2048
	ds_read_b128 v[208:211], v90 offset:3072
	global_load_lds_dwordx4 v[212:213], off
	v_lshl_add_u64 v[212:213], v[214:215], 0, s[4:5]
	s_mov_b32 m0, s42
	s_nop 0
	global_load_lds_dwordx4 v[212:213], off
	s_barrier
; #define PG8_STAGE(bufoff, gbase, voff) do { _Pragma("unroll") for (int _i = 0; _i < 2; ++_i) \
;         __builtin_amdgcn_global_load_lds((const unsigned*)((const char*)(gbase) + (voff)[_i]), (LAS unsigned*)(lds + (bufoff) + ldsw + _i * 8192), 16, 0, 0); } while (0)
; #define PG8_LDA(dst, b, h) do { _Pragma("unroll") for (int m = 0; m < 4; ++m) _Pragma("unroll") for (int k = 0; k < 2; ++k) dst[m][k] = *(const LAS bf16x8*)(lds + PG8_SA(b, h) + aoff + m * 2048 + k * 1024); } while (0)
; #define PG8_MMA(ai, bj, At, Bt) do { __builtin_amdgcn_s_setprio(1); _Pragma("unroll") for (int m = 0; m < 4; ++m) _Pragma("unroll") for (int n = 0; n < 2; ++n) _Pragma("unroll") for (int k = 0; k < 2; ++k) \
;         acc[ai][bj][m][n] = __builtin_amdgcn_mfma_f32_16x16x32_bf16(Bt[n][k], At[m][k], acc[ai][bj][m][n], 0, 0, 0); __builtin_amdgcn_s_setprio(0); } while (0)
; #define PG8_WAIT_V(n) asm volatile("s_waitcnt vmcnt(" #n ")" ::: "memory")
; #define PG8_WAIT_L(n) asm volatile("s_waitcnt lgkmcnt(" #n ")" ::: "memory")
; #define PG8_BAR __builtin_amdgcn_s_barrier()
; #define PG8_SCHED __builtin_amdgcn_sched_barrier(0)
; template <class Epi, class Sched, bool ZERO>
; __device__ __forceinline__ void gemm_phase_acc(LAS unsigned char* lds, const Gemm g, const Sched& S, const Epi& E, f32x4 (&acc)[2][2][4][2]) {
;     ...
;             PG8_BAR; PG8_WAIT_L(0); PG8_MMA(0, 1, At, B1); PG8_BAR;
;             PG8_LDA(At, 1, 1); PG8_STAGE(PG8_SA(1, 0), a3, voffA);
;             PG8_BAR; PG8_WAIT_L(0); PG8_MMA(1, 0, At, B0); PG8_BAR; PG8_SCHED;
;             PG8_STAGE(PG8_SB(1, 1), b3 + hstep, voffB);
;             PG8_WAIT_V(6); PG8_BAR; PG8_MMA(1, 1, At, B1); PG8_BAR;
;         }
;         if constexpr (!Epi::AFTER_DRAIN) E(acc, cur, wr, wc, fr, fq);
;         if constexpr (Epi::DRAIN) __builtin_amdgcn_s_waitcnt(0x0F70);
;         if (!has_next) break;
	s_waitcnt lgkmcnt(0)
	s_setprio 1
	s_waitcnt lgkmcnt(0)
	v_mfma_f32_16x16x32_bf16 v[148:151], v[196:199], v[164:167], v[148:151]
	v_mfma_f32_16x16x32_bf16 v[144:147], v[204:207], v[164:167], v[144:147]
	v_mfma_f32_16x16x32_bf16 v[132:135], v[196:199], v[172:175], v[132:135]
	v_mfma_f32_16x16x32_bf16 v[128:131], v[204:207], v[172:175], v[128:131]
	v_mfma_f32_16x16x32_bf16 v[108:111], v[196:199], v[180:183], v[108:111]
	v_mfma_f32_16x16x32_bf16 v[104:107], v[204:207], v[180:183], v[104:107]
	v_mfma_f32_16x16x32_bf16 v[80:83], v[196:199], v[188:191], v[80:83]
	v_mfma_f32_16x16x32_bf16 v[76:79], v[204:207], v[188:191], v[76:79]
	v_mfma_f32_16x16x32_bf16 v[148:151], v[200:203], v[168:171], v[148:151]
	v_mfma_f32_16x16x32_bf16 v[144:147], v[208:211], v[168:171], v[144:147]
	v_mfma_f32_16x16x32_bf16 v[132:135], v[200:203], v[176:179], v[132:135]
	v_mfma_f32_16x16x32_bf16 v[128:131], v[208:211], v[176:179], v[128:131]
	v_mfma_f32_16x16x32_bf16 v[108:111], v[200:203], v[184:187], v[108:111]
	v_mfma_f32_16x16x32_bf16 v[104:107], v[208:211], v[184:187], v[104:107]
	v_mfma_f32_16x16x32_bf16 v[80:83], v[200:203], v[192:195], v[80:83]
	v_mfma_f32_16x16x32_bf16 v[76:79], v[208:211], v[192:195], v[76:79]
	s_setprio 0
	s_mov_b32 m0, s24
	v_lshl_add_u64 v[212:213], v[216:217], 0, s[4:5]
	s_barrier
	ds_read_b128 v[164:167], v87 offset:49152
	ds_read_b128 v[168:171], v87 offset:50176
	ds_read_b128 v[172:175], v87 offset:51200
	ds_read_b128 v[176:179], v87 offset:52224
	ds_read_b128 v[180:183], v87 offset:53248
	ds_read_b128 v[184:187], v87 offset:54272
	ds_read_b128 v[188:191], v87 offset:55296
	ds_read_b128 v[192:195], v87 offset:56320
	global_load_lds_dwordx4 v[212:213], off
	v_lshl_add_u64 v[212:213], v[218:219], 0, s[4:5]
	s_mov_b32 m0, s25
	s_nop 0
	global_load_lds_dwordx4 v[212:213], off
	s_barrier
	s_waitcnt lgkmcnt(0)
	s_setprio 1
	s_waitcnt lgkmcnt(0)
	v_mfma_f32_16x16x32_bf16 v[68:71], v[100:103], v[164:167], v[68:71]
	v_mfma_f32_16x16x32_bf16 v[64:67], v[124:127], v[164:167], v[64:67]
	v_mfma_f32_16x16x32_bf16 v[44:47], v[100:103], v[172:175], v[44:47]
	v_mfma_f32_16x16x32_bf16 v[40:43], v[124:127], v[172:175], v[40:43]
	v_mfma_f32_16x16x32_bf16 v[28:31], v[100:103], v[180:183], v[28:31]
	v_mfma_f32_16x16x32_bf16 v[24:27], v[124:127], v[180:183], v[24:27]
	v_mfma_f32_16x16x32_bf16 v[12:15], v[100:103], v[188:191], v[12:15]
	v_mfma_f32_16x16x32_bf16 v[8:11], v[124:127], v[188:191], v[8:11]
	v_mfma_f32_16x16x32_bf16 v[68:71], v[112:115], v[168:171], v[68:71]
	v_mfma_f32_16x16x32_bf16 v[64:67], v[160:163], v[168:171], v[64:67]
	v_mfma_f32_16x16x32_bf16 v[44:47], v[112:115], v[176:179], v[44:47]
	v_mfma_f32_16x16x32_bf16 v[40:43], v[160:163], v[176:179], v[40:43]
	v_mfma_f32_16x16x32_bf16 v[28:31], v[112:115], v[184:187], v[28:31]
	v_mfma_f32_16x16x32_bf16 v[24:27], v[160:163], v[184:187], v[24:27]
	v_mfma_f32_16x16x32_bf16 v[12:15], v[112:115], v[192:195], v[12:15]
	v_mfma_f32_16x16x32_bf16 v[8:11], v[160:163], v[192:195], v[8:11]
	s_setprio 0
	s_barrier
	s_add_u32 s6, s6, 0x40080
	s_addc_u32 s7, s7, 0
	s_mov_b32 m0, s43
	v_lshl_add_u64 v[100:101], s[6:7], 0, v[50:51]
	global_load_lds_dwordx4 v[100:101], off
	v_lshl_add_u64 v[100:101], s[6:7], 0, v[62:63]
	s_mov_b32 m0, s44
	s_nop 0
	global_load_lds_dwordx4 v[100:101], off
	s_waitcnt vmcnt(6)
	s_barrier
	s_setprio 1
	v_mfma_f32_16x16x32_bf16 v[56:59], v[196:199], v[164:167], v[56:59]
	v_mfma_f32_16x16x32_bf16 v[52:55], v[204:207], v[164:167], v[52:55]
	v_mfma_f32_16x16x32_bf16 v[36:39], v[196:199], v[172:175], v[36:39]
	v_mfma_f32_16x16x32_bf16 v[32:35], v[204:207], v[172:175], v[32:35]
	v_mfma_f32_16x16x32_bf16 v[20:23], v[196:199], v[180:183], v[20:23]
	v_mfma_f32_16x16x32_bf16 v[16:19], v[204:207], v[180:183], v[16:19]
	v_mfma_f32_16x16x32_bf16 v[4:7], v[196:199], v[188:191], v[4:7]
	v_mfma_f32_16x16x32_bf16 v[0:3], v[204:207], v[188:191], v[0:3]
	v_mfma_f32_16x16x32_bf16 v[56:59], v[200:203], v[168:171], v[56:59]
	v_mfma_f32_16x16x32_bf16 v[52:55], v[208:211], v[168:171], v[52:55]
	v_mfma_f32_16x16x32_bf16 v[36:39], v[200:203], v[176:179], v[36:39]
	v_mfma_f32_16x16x32_bf16 v[32:35], v[208:211], v[176:179], v[32:35]
	v_mfma_f32_16x16x32_bf16 v[20:23], v[200:203], v[184:187], v[20:23]
	v_mfma_f32_16x16x32_bf16 v[16:19], v[208:211], v[184:187], v[16:19]
	v_mfma_f32_16x16x32_bf16 v[4:7], v[200:203], v[192:195], v[4:7]
	v_mfma_f32_16x16x32_bf16 v[0:3], v[208:211], v[192:195], v[0:3]
	s_setprio 0
	s_add_i32 s28, s28, 2
	s_add_u32 s2, s2, 0x100
	s_addc_u32 s3, s3, 0
	s_cmp_gt_u32 s28, 13
	s_barrier
	s_cbranch_scc0 .LBB0_631
	v_cmp_eq_u32_e32 vcc, 0, v224
	s_and_saveexec_b64 s[48:49], vcc
	s_cbranch_execz .Lgb3z_done
	s_add_u32 s44, s70, 0xff83500
	s_addc_u32 s45, s71, 0
	s_mov_b32 s46, 0x8000
	v_mov_b32_e32 v250, 0

; __device__ __forceinline__ void run_phase(const Params& p, LAS unsigned char* lds, int ph) {
;     ...
;             if (threadIdx.x < 64) { unsigned spins = 0;
;                 while ((unsigned)__builtin_amdgcn_readfirstlane(__hip_atomic_load(flags + 64 * (pmt * 2 + j - 2), __ATOMIC_RELAXED, __HIP_MEMORY_SCOPE_AGENT)) == 0u) { __builtin_amdgcn_s_sleep(2); if (++spins > (1u << 22)) break; }
;                 __builtin_amdgcn_fence(__ATOMIC_ACQUIRE, "agent"); asm volatile("s_waitcnt vmcnt(0)" ::: "memory"); }
.Lgb3z_ok:
	s_lshl_b32 s50, s18, 9
	s_lshl_b32 s51, s34, 8
	s_add_i32 s50, s50, s51
	s_add_i32 s50, s50, 0xff87e00
	s_add_u32 s44, s70, s50
	s_addc_u32 s45, s71, 0
	s_mov_b32 s46, 0x8000
.Lgb3z_fspin:
	global_load_dword v251, v250, s[44:45] sc1
	s_waitcnt vmcnt(0)
	v_readfirstlane_b32 s47, v251
	s_cmp_lg_u32 s47, 0
	s_cbranch_scc1 .Lgb3z_fok
	s_sleep 2
	s_sub_u32 s46, s46, 1
	s_cmp_lg_u32 s46, 0
	s_cbranch_scc1 .Lgb3z_fspin

;     __device__ __forceinline__ void operator()(const f32x4 (&acc)[2][2][4][2], const Unit& u, int wr, int wc, int fr, int fq) const {
;     ...
;         const bf16_t* ldp = nullptr; bf16_t* stp; bool ld_lm = false, st_lm = false, act_silu = false, recip = false; int ld = 0;
;         if (wt < 16) { bf16_t* t = (bf16_t*)(ws + OFF_Q) + (size_t)(u.pm * 4 + (wt - 12)) * 65536 + gl_off; ldp = t; stp = t; ld_lm = st_lm = true; }
;         else if (wt < 20) { ldp = (const bf16_t*)(ws + OFF_Q) + (size_t)(u.pm * 4 + (wt - 16)) * 65536 + gl_off; ld_lm = true; stp = am + (wt - 16) * 256; ld = 1024; act_silu = true; }
;         else if (wt < 24) { bf16_t* t = (bf16_t*)(ws + OFF_PM) + (wt - 22) * 256; ldp = t; stp = t; ld = 512; act_silu = true; }
;         else if (wt < 28) { stp = (bf16_t*)(ws + OFF_GB) + (size_t)(u.pm * 8 + (wt - 24)) * 65536 + gl_off; st_lm = true; }
;         else { bf16_t* t = (bf16_t*)(ws + OFF_GB) + (size_t)(u.pm * 8 + (wt - 24)) * 65536 + gl_off; stp = t; st_lm = true; ldp = t - 4 * 65536; ld_lm = true; recip = true; }
; #pragma unroll
;         for (int ai = 0; ai < 2; ++ai) {
;             u32x4 old8[4][2];
;             if (ldp) {
; #pragma unroll
;                 for (int m = 0; m < 4; ++m)
; #pragma unroll
;                     for (int bj = 0; bj < 2; ++bj) old8[m][bj] = ld_lm ? *(const u32x4*)(ldp + ((ai * 4 + m) * 2 + bj) * 512)
;                                                                        : *(const u32x4*)(ldp + (size_t)(row0 + ai * 128 + m * 16) * ld + col0 + bj * 128);
;             }
.Lgb3z_done:
	s_or_b64 exec, exec, s[48:49]
	s_barrier
	v_readlane_b32 s0, v254, 30
	s_lshl_b32 s0, s0, 9
	s_add_u32 s0, s70, s0
	s_addc_u32 s1, s71, 0
	v_lshl_add_u32 v160, s18, 8, v85
	s_add_u32 s2, s0, 0x93f4400
	s_addc_u32 s3, s1, 0
	v_lshl_or_b32 v48, s17, 6, v84
	v_mov_b32_e32 v49, 0
	v_ashrrev_i32_e32 v161, 31, v160
	s_cmp_lg_u64 s[2:3], 0
	v_lshl_add_u64 v[162:163], s[2:3], 0, v[48:49]
	v_lshlrev_b64 v[48:49], 9, v[160:161]
	s_cselect_b64 s[0:1], -1, 0
	s_cmp_eq_u64 s[2:3], 0
	v_lshl_add_u64 v[170:171], v[48:49], 1, v[162:163]
	v_or_b32_e32 v168, 16, v160
	v_or_b32_e32 v166, 32, v160
	v_or_b32_e32 v164, 48, v160
	s_cbranch_scc1 .LBB0_634
	v_ashrrev_i32_e32 v169, 31, v168
	v_lshlrev_b64 v[48:49], 10, v[168:169]
	v_lshl_add_u64 v[48:49], v[162:163], 0, v[48:49]
	v_ashrrev_i32_e32 v167, 31, v166
	global_load_dwordx4 v[124:127], v[170:171], off
	global_load_dwordx4 v[112:115], v[170:171], off offset:256
	global_load_dwordx4 v[100:103], v[48:49], off
	global_load_dwordx4 v[88:91], v[48:49], off offset:256
	v_lshlrev_b64 v[48:49], 10, v[166:167]
	v_lshl_add_u64 v[48:49], v[162:163], 0, v[48:49]
	v_ashrrev_i32_e32 v165, 31, v164
	global_load_dwordx4 v[84:87], v[48:49], off
	global_load_dwordx4 v[72:75], v[48:49], off offset:256
	v_lshlrev_b64 v[48:49], 10, v[164:165]
	v_lshl_add_u64 v[48:49], v[162:163], 0, v[48:49]
	global_load_dwordx4 v[60:63], v[48:49], off
	s_nop 0
	global_load_dwordx4 v[48:51], v[48:49], off offset:256
	s_branch .LBB0_635

; #define LAS __attribute__((address_space(3)))
; __device__ __forceinline__ void run_phase(const Params& p, LAS unsigned char* lds, int ph) {
;     ...
;         passB_unit(p, lds, c4 * 2); passB_unit(p, lds, c4 * 2 + 1);
;         if (j < 2) {
;             LAS float* T = (LAS float*)lds; const int w128 = pmt * 2 + j;
;             for (int job = w128; job < 640; job += 128) {
;                 if (job < 256) { const int kt = job & 15, ntile = job >> 4; transpose_tile(p.branch_m_w, 1024, kt * 64, ntile * 64, (bf16_t*)(p.ws + OFF_WMT), 1024, ntile * 64, T); }
;                 else if (job < 512) { const int j2 = job - 256; const int kt = j2 & 15, ntile = j2 >> 4; transpose_tile(p.out_w, 1024, kt * 64, ntile * 64, (bf16_t*)(p.ws + OFF_WOT), 1024, ntile * 64, T); }
;                 else { const int j2 = job - 512; const int kt = j2 & 7, ntile = j2 >> 3; transpose_tile(p.branch_p_w, 1024, kt * 64, ntile * 64, (bf16_t*)(p.ws + OFF_WPT), 512, ntile * 64, T); }
;             }
;         }
;         if (j >= 2) {
;             if (threadIdx.x < 64) { unsigned spins = 0;
;                 while ((unsigned)__builtin_amdgcn_readfirstlane(__hip_atomic_load(flags + 64 * (pmt * 2 + j - 2), __ATOMIC_RELAXED, __HIP_MEMORY_SCOPE_AGENT)) == 0u) { __builtin_amdgcn_s_sleep(2); if (++spins > (1u << 22)) break; }
;                 __builtin_amdgcn_fence(__ATOMIC_ACQUIRE, "agent"); asm volatile("s_waitcnt vmcnt(0)" ::: "memory"); }
;             __syncthreads();
;             SchedOne S{pmt, 72 + 22 + (j - 2)}; EpiG2 E{p.ws, (bf16_t*)p.out};
;             pg8::gemm_phase(lds, pg8::Gemm{AB, AB, 1024}, S, E);
.LBB0_671:
	s_barrier
	v_readlane_b32 s2, v254, 40
	v_readlane_b32 s3, v254, 41
	v_readlane_b32 s8, v254, 42
	v_readlane_b32 s9, v254, 43
	v_readlane_b32 s14, v254, 44
	v_readlane_b32 s15, v254, 45
	v_readlane_b32 s16, v254, 46
	v_readlane_b32 s17, v254, 47
	v_readlane_b32 s27, v254, 48
	v_readlane_b32 s30, v254, 49
	v_readlane_b32 s31, v254, 50
	v_readlane_b32 s38, v254, 51
	v_readlane_b32 s39, v254, 52
	v_mbcnt_lo_u32_b32 v158, -1, 0
	s_branch .LBB0_533

; __device__ __forceinline__ unsigned xb_ld(unsigned* p)              { return __hip_atomic_load(p, __ATOMIC_RELAXED, __HIP_MEMORY_SCOPE_AGENT); }
; #define XB_SPIN(cond, bar) do { unsigned _sp = 0; while (cond) { __builtin_amdgcn_s_sleep(1); \
;     if ((++_sp & 255u) == 0u) { if (xb_ld(&(bar)[XB_TMO])) break; if (_sp > XB_SPIN_CAP) { atomicAdd(&(bar)[XB_TMO], 1u); break; } } } } while (0)
; __device__ __forceinline__ void xcd_barrier(const XcdBarrier& b) {
;     ...
;             XB_SPIN(xb_ld(&bar[XB_XGEN(b.x)]) == gen, bar);
;             __builtin_amdgcn_fence(__ATOMIC_ACQUIRE, "agent");
;             asm volatile("s_waitcnt vmcnt(0)" ::: "memory");
;         }
;     }
;     __syncthreads();
.LBB0_1034:
	s_or_b64 exec, exec, s[0:1]
	s_waitcnt lgkmcnt(0)
	v_mov_b32_e32 v0, v224
	v_cmp_eq_u32_e32 vcc, 0, v224
	s_and_saveexec_b64 s[44:45], vcc
	s_cbranch_execz .Lgb6_done
	s_add_u32 s40, s70, 0xff83500
	s_addc_u32 s41, s71, 0
	s_mov_b32 s42, 0x8000
	v_mov_b32_e32 v250, 0
.Lgb6_spin:
	global_load_dword v251, v250, s[40:41] sc1
	s_waitcnt vmcnt(0)
	v_readfirstlane_b32 s43, v251
	s_cmp_ge_u32 s43, 6
	s_cbranch_scc1 .Lgb6_ok
	s_sleep 1
	s_sub_u32 s42, s42, 1
	s_cmp_lg_u32 s42, 0
	s_cbranch_scc1 .Lgb6_spin

; __device__ __forceinline__ int opaque_tid() { int t = (int)threadIdx.x; asm volatile("" : "+v"(t)); return t; }
; #define PG8_STAGE(bufoff, gbase, voff) do { _Pragma("unroll") for (int _i = 0; _i < 2; ++_i) \
;         __builtin_amdgcn_global_load_lds((const unsigned*)((const char*)(gbase) + (voff)[_i]), (LAS unsigned*)(lds + (bufoff) + ldsw + _i * 8192), 16, 0, 0); } while (0)
; #define PG8_WAIT_V(n) asm volatile("s_waitcnt vmcnt(" #n ")" ::: "memory")
; #define PG8_BAR __builtin_amdgcn_s_barrier()
; template <class Epi, class Sched, bool ZERO>
; __device__ __forceinline__ void gemm_phase_acc(LAS unsigned char* lds, const Gemm g, const Sched& S, const Epi& E, f32x4 (&acc)[2][2][4][2]) {
;     const int tid = opaque_tid(), wid = __builtin_amdgcn_readfirstlane(tid >> 6), lane = tid & 63, wr = wid >> 2, wc = wid & 3, fr = lane & 15, fq = lane >> 4;
;     const int K = g.K, nt = K / BK;
;     unsigned voffA[2], voffB[2];
; #pragma unroll
;     for (int i = 0; i < 2; ++i) { int R, C; stage_rc(tid * 16 + i * 8192, R, C); const int Rb = (R & ~31) + perm32(R & 31);
;         voffA[i] = (unsigned)(R * K + C) * 2u; voffB[i] = (unsigned)(Rb * K + C) * 2u; }
;     const size_t kstep = (size_t)(BK * 2);
;     const size_t hstep = (size_t)HALF * K * 2;
;     const size_t tstep = 2 * hstep;
;     const unsigned ldsw = (unsigned)wid * 1024u;
;     const int aoff = lds_byte(wr * 64 + fr, fq * 8), boff = lds_byte(wc * 32 + fr, fq * 8);
;     ...
;     Unit cur, nxt; int ui = 0;
;     if (!S.next(0, cur)) return;
;     if constexpr (ZERO) {
; #pragma unroll
;     for (int a = 0; a < 2; ++a)
; #pragma unroll
;         for (int b = 0; b < 2; ++b)
; #pragma unroll
;             for (int m = 0; m < 4; ++m)
; #pragma unroll
;                 for (int n = 0; n < 2; ++n) acc[a][b][m][n] = (f32x4){0.f, 0.f, 0.f, 0.f};
;     }
;     bf16x8 At[4][2], B0[2][2], B1[2][2];
;     const char* cA = (const char*)g.A + (size_t)cur.pm * tstep; const char* cB = (const char*)g.Bt + (size_t)cur.pn * tstep;
;     PG8_STAGE(PG8_SB(0, 0), cB, voffB); PG8_STAGE(PG8_SA(0, 0), cA, voffA); PG8_STAGE(PG8_SB(0, 1), cB + hstep, voffB); PG8_STAGE(PG8_SA(0, 1), cA + hstep, voffA);
;     if (wr == 1) PG8_BAR;
;     PG8_WAIT_V(4); PG8_BAR;
;     PG8_STAGE(PG8_SB(1, 0), cB + kstep, voffB); PG8_STAGE(PG8_SA(1, 0), cA + kstep, voffA); PG8_STAGE(PG8_SB(1, 1), cB + hstep + kstep, voffB);
;     PG8_WAIT_V(6); PG8_BAR;
.Lgb6_done:
	s_or_b64 exec, exec, s[44:45]
	s_barrier
	s_mov_b32 s0, 0x1fffe0
	v_lshlrev_b32_e32 v0, 4, v224
	v_add_u32_e32 v1, 0x2000, v0
	v_ashrrev_i32_e32 v2, 31, v1
	v_lshrrev_b32_e32 v2, 22, v2
	v_add_u32_e32 v2, v1, v2
	v_ashrrev_i32_e32 v8, 10, v2
	v_mul_i32_i24_e32 v2, 0x400, v8
	v_sub_u32_e32 v1, v1, v2
	v_lshrrev_b32_e32 v2, 4, v1
	v_bitop3_b32 v1, v2, v1, 32 bitop3:0x6c
	v_ashrrev_i32_e32 v2, 31, v1
	v_lshrrev_b32_e32 v2, 26, v2
	v_add_u32_e32 v2, v1, v2
	v_lshlrev_b32_e32 v3, 3, v8
	v_ashrrev_i32_e32 v9, 6, v2
	v_and_b32_e32 v3, -16, v3
	v_add_u32_e32 v3, v9, v3
	v_and_b32_e32 v4, 3, v9
	v_lshrrev_b32_e32 v5, 2, v3
	v_lshlrev_b32_e32 v6, 1, v3
	v_and_b32_e32 v2, 0xc0, v2
	v_and_or_b32 v4, v3, s0, v4
	v_and_b32_e32 v5, 4, v5
	v_and_b32_e32 v6, 24, v6
	v_sub_u32_e32 v1, v1, v2
	v_mov_b32_e32 v2, 1
	v_or3_b32 v4, v4, v5, v6
	v_lshlrev_b32_e32 v5, 5, v8
	v_ashrrev_i16_sdwa v1, v2, sext(v1) dst_sel:DWORD dst_unused:UNUSED_PAD src0_sel:DWORD src1_sel:BYTE_0
	v_and_b32_e32 v5, 32, v5
	v_bfe_i32 v10, v1, 0, 16
	v_add_lshl_u32 v1, v5, v10, 1
	v_lshl_add_u32 v128, v4, 11, v1
	v_lshl_add_u32 v130, v3, 11, v1
	v_bfe_i32 v1, v224, 27, 1
	v_lshrrev_b32_e32 v1, 22, v1
	v_add_u32_e32 v1, v0, v1
	v_and_b32_e32 v1, 0xfffffc00, v1
	v_sub_u32_e32 v0, v0, v1
	v_lshrrev_b32_e32 v1, 4, v0
	v_bitop3_b32 v1, v1, v0, 32 bitop3:0x6c
	v_ashrrev_i32_e32 v0, 31, v0
	v_lshrrev_b32_e32 v0, 26, v0
	v_add_u32_e32 v0, v1, v0
	v_ashrrev_i32_e32 v11, 6, v0
	v_ashrrev_i32_e32 v0, 31, v224
	v_lshrrev_b32_e32 v0, 26, v0
	v_add_u32_e32 v0, v224, v0
	v_ashrrev_i32_e32 v12, 6, v0
	v_lshlrev_b32_e32 v0, 3, v12
	v_and_b32_e32 v0, -16, v0
	v_add_u32_e32 v0, v11, v0
	v_readfirstlane_b32 s14, v224
	v_and_b32_e32 v3, 3, v11
	v_lshrrev_b32_e32 v4, 2, v0
	v_lshlrev_b32_e32 v5, 1, v0
	s_ashr_i32 s4, s14, 6
	v_and_or_b32 v3, v0, s0, v3
	v_and_b32_e32 v4, 4, v4
	v_and_b32_e32 v5, 24, v5
	s_ashr_i32 s12, s14, 8
	s_lshl_b32 s8, s4, 10
	v_or3_b32 v3, v3, v4, v5
	v_mul_i32_i24_e32 v5, 64, v11
	v_sub_u32_e32 v1, v1, v5
	s_add_u32 s5, s70, s19
	v_lshlrev_b32_e32 v4, 5, v12
	v_ashrrev_i16_sdwa v1, v2, sext(v1) dst_sel:DWORD dst_unused:UNUSED_PAD src0_sel:DWORD src1_sel:BYTE_0
	s_addc_u32 s7, s71, 0
	v_and_b32_e32 v4, 32, v4
	v_bfe_i32 v13, v1, 0, 16
	s_add_u32 s0, s5, 0x2700000
	v_add_lshl_u32 v1, v4, v13, 1
	s_addc_u32 s1, s7, 0
	s_add_i32 s15, s8, 0
	v_lshl_add_u32 v132, v3, 11, v1
	s_add_i32 m0, s15, 0x10000
	v_readlane_b32 s2, v254, 26
	global_load_lds_dwordx4 v132, s[0:1]
	s_add_i32 m0, s15, 0x12000
	v_readlane_b32 s6, v254, 31
	v_readlane_b32 s3, v254, 27
	s_add_u32 s2, s6, s2
	v_readlane_b32 s6, v254, 32
	v_lshl_add_u32 v134, v0, 11, v1
	global_load_lds_dwordx4 v128, s[0:1]
	s_addc_u32 s3, s6, s3
	s_mov_b32 m0, s15
	s_add_i32 s16, s15, 0x2000
	global_load_lds_dwordx4 v134, s[2:3]
	s_mov_b32 m0, s16
	s_add_u32 s6, s5, 0x2740000
	global_load_lds_dwordx4 v130, s[2:3]
	s_addc_u32 s7, s7, 0
	s_add_i32 m0, s15, 0x14000
	v_mov_b32_e32 v133, 0
	global_load_lds_dwordx4 v132, s[6:7]
	s_add_i32 m0, s15, 0x16000
	v_mov_b32_e32 v129, v133
	global_load_lds_dwordx4 v128, s[6:7]
	s_add_u32 s6, s2, 0x40000
	s_addc_u32 s7, s3, 0
	s_add_i32 s24, s15, 0x4000
	s_mov_b32 m0, s24
	s_add_i32 s25, s15, 0x6000
	global_load_lds_dwordx4 v134, s[6:7]
	s_mov_b32 m0, s25
	v_mov_b32_e32 v135, v133
	global_load_lds_dwordx4 v130, s[6:7]
	v_mov_b32_e32 v131, v133
	v_lshl_add_u64 v[6:7], s[0:1], 0, v[132:133]
	v_lshl_add_u64 v[4:5], s[0:1], 0, v[128:129]
	v_lshl_add_u64 v[2:3], s[2:3], 0, v[134:135]
	s_cmp_lg_u32 s12, 1
	v_lshl_add_u64 v[0:1], s[2:3], 0, v[130:131]
	s_cbranch_scc1 .LBB0_1036
	s_barrier
